# NSA sliding-window loop: next block K/V fragments prefetched by LDS-DMA during current block, read back via ds_read_b128
# speedup vs baseline: 1.0574x; 1.0024x over previous
.LBB0_400:
	s_mov_b32 s75, s49
	v_lshl_add_u64 v[140:141], v[136:137], 0, s[74:75]
	s_mov_b32 s73, s49
	v_lshl_add_u64 v[136:137], v[136:137], 0, s[72:73]
	global_load_ushort v120, v[140:141], off offset:2562
	global_load_ushort v121, v[136:137], off offset:2562
	global_load_ushort v124, v[136:137], off offset:2568
	global_load_ushort v125, v[136:137], off offset:2574
	ds_bpermute_b32 v122, v167, v147
	ds_bpermute_b32 v123, v167, v146
	v_lshlrev_b32_e32 v100, 16, v129
	v_and_b32_e32 v101, 0xffff0000, v129
	v_lshlrev_b32_e32 v118, 16, v185
	s_waitcnt lgkmcnt(1)
	v_add_f32_e32 v122, v147, v122
	ds_bpermute_b32 v126, v166, v122
	s_waitcnt lgkmcnt(1)
	v_add_f32_e32 v123, v146, v123
	ds_bpermute_b32 v127, v166, v123
	v_and_b32_e32 v119, 0xffff0000, v185
	v_lshlrev_b32_e32 v96, 16, v189
	s_waitcnt lgkmcnt(1)
	v_add_f32_e32 v122, v122, v126
	v_and_b32_e32 v97, 0xffff0000, v189
	s_waitcnt lgkmcnt(0)
	v_add_f32_e32 v123, v123, v127
	v_lshlrev_b32_e32 v102, 16, v193
	v_and_b32_e32 v103, 0xffff0000, v193
	v_lshlrev_b32_e32 v106, 16, v195
	v_and_b32_e32 v107, 0xffff0000, v195
	v_lshlrev_b32_e32 v116, 16, v186
	v_and_b32_e32 v117, 0xffff0000, v186
	v_lshlrev_b32_e32 v112, 16, v188
	v_and_b32_e32 v113, 0xffff0000, v188
	v_lshlrev_b32_e32 v110, 16, v194
	v_and_b32_e32 v111, 0xffff0000, v194
	v_lshlrev_b32_e32 v108, 16, v192
	v_and_b32_e32 v109, 0xffff0000, v192
	v_lshlrev_b32_e32 v104, 16, v190
	v_and_b32_e32 v105, 0xffff0000, v190
	v_lshlrev_b32_e32 v114, 16, v187
	v_and_b32_e32 v115, 0xffff0000, v187
	v_lshlrev_b32_e32 v98, 16, v191
	v_and_b32_e32 v99, 0xffff0000, v191
	v_mov_b32_e32 v139, 0
	s_waitcnt vmcnt(3)
	v_lshlrev_b32_e32 v120, 16, v120
	v_mul_f32_e32 v120, 0xbfb8aa3b, v120
	v_exp_f32_e32 v120, v120
	s_waitcnt vmcnt(2)
	v_lshlrev_b32_e32 v121, 16, v121
	v_mul_f32_e32 v121, 0xbfb8aa3b, v121
	v_exp_f32_e32 v121, v121
	v_add_f32_e32 v120, 1.0, v120
	v_div_scale_f32 v126, s[0:1], v120, v120, 1.0
	v_rcp_f32_e32 v131, v126
	v_div_scale_f32 v127, vcc, 1.0, v120, 1.0
	v_add_f32_e32 v121, 1.0, v121
	v_fma_f32 v147, -v126, v131, 1.0
	v_fmac_f32_e32 v131, v147, v131
	v_mul_f32_e32 v147, v127, v131
	v_div_scale_f32 v129, s[0:1], v121, v121, 1.0
	v_fma_f32 v180, -v126, v147, v127
	v_rcp_f32_e32 v138, v129
	v_fmac_f32_e32 v147, v180, v131
	v_fma_f32 v126, -v126, v147, v127
	v_div_fmas_f32 v126, v126, v131, v147
	v_div_fixup_f32 v120, v126, v120, 1.0
	v_fma_f32 v152, -v129, v138, 1.0
	v_div_scale_f32 v126, s[0:1], v122, v122, v120
	v_div_scale_f32 v146, s[6:7], 1.0, v121, 1.0
	v_fmac_f32_e32 v138, v152, v138
	v_rcp_f32_e32 v127, v126
	v_mul_f32_e32 v152, v146, v138
	v_fma_f32 v185, -v129, v152, v146
	v_fmac_f32_e32 v152, v185, v138
	v_fma_f32 v129, -v129, v152, v146
	v_fma_f32 v146, -v126, v127, 1.0
	v_div_scale_f32 v131, vcc, v120, v122, v120
	v_fmac_f32_e32 v127, v146, v127
	v_mul_f32_e32 v146, v131, v127
	v_fma_f32 v147, -v126, v146, v131
	v_fmac_f32_e32 v146, v147, v127
	v_fma_f32 v126, -v126, v146, v131
	v_div_fmas_f32 v126, v126, v127, v146
	s_mov_b64 vcc, s[6:7]
	v_div_fixup_f32 v120, v126, v122, v120
	v_div_fmas_f32 v126, v129, v138, v152
	v_cmp_lt_f32_e32 vcc, 0, v122
	v_div_fixup_f32 v121, v126, v121, 1.0
	v_mov_b32_e32 v138, v139
	v_cndmask_b32_e32 v120, 0, v120, vcc
	v_pk_fma_f32 v[92:93], v[92:93], v[120:121], v[96:97] op_sel_hi:[1,0,1]
	v_pk_fma_f32 v[84:85], v[84:85], v[120:121], v[102:103] op_sel_hi:[1,0,1]
	v_div_scale_f32 v96, s[0:1], v123, v123, v121
	v_cvt_pk_bf16_f32 v204, v84, v85
	v_rcp_f32_e32 v84, v96
	v_pk_fma_f32 v[80:81], v[80:81], v[120:121], v[106:107] op_sel_hi:[1,0,1]
	v_div_scale_f32 v97, vcc, v121, v123, v121
	v_cvt_pk_bf16_f32 v203, v80, v81
	v_fma_f32 v80, -v96, v84, 1.0
	v_fmac_f32_e32 v84, v80, v84
	v_mul_f32_e32 v80, v97, v84
	v_fma_f32 v81, -v96, v80, v97
	v_fmac_f32_e32 v80, v81, v84
	v_fma_f32 v81, -v96, v80, v97
	v_div_fmas_f32 v80, v81, v84, v80
	v_div_fixup_f32 v80, v80, v123, v121
	v_cmp_lt_f32_e32 vcc, 0, v123
	v_pk_fma_f32 v[94:95], v[94:95], v[120:121], v[100:101] op_sel_hi:[1,0,1]
	v_pk_fma_f32 v[90:91], v[90:91], v[120:121], v[104:105] op_sel_hi:[1,0,1]
	v_cndmask_b32_e32 v80, 0, v80, vcc
	v_pk_fma_f32 v[74:75], v[74:75], v[80:81], v[118:119] op_sel_hi:[1,0,1]
	v_pk_fma_f32 v[72:73], v[72:73], v[80:81], v[116:117] op_sel_hi:[1,0,1]
	v_cvt_pk_bf16_f32 v198, v74, v75
	v_lshlrev_b32_e32 v74, 16, v178
	v_and_b32_e32 v75, 0xffff0000, v178
	v_pk_fma_f32 v[70:71], v[70:71], v[80:81], v[74:75] op_sel_hi:[1,0,1]
	v_cvt_pk_bf16_f32 v199, v72, v73
	v_lshlrev_b32_e32 v72, 16, v179
	v_cvt_pk_bf16_f32 v195, v70, v71
	s_waitcnt vmcnt(1)
	v_lshlrev_b32_e32 v70, 16, v124
	v_and_b32_e32 v73, 0xffff0000, v179
	v_mul_f32_e32 v70, 0xbfb8aa3b, v70
	v_pk_fma_f32 v[68:69], v[68:69], v[80:81], v[72:73] op_sel_hi:[1,0,1]
	v_exp_f32_e32 v72, v70
	ds_bpermute_b32 v71, v167, v143
	v_pk_fma_f32 v[76:77], v[76:77], v[80:81], v[112:113] op_sel_hi:[1,0,1]
	v_lshlrev_b32_e32 v70, 16, v177
	v_add_f32_e32 v72, 1.0, v72
	v_div_scale_f32 v75, s[0:1], v72, v72, 1.0
	v_cvt_pk_bf16_f32 v201, v76, v77
	s_waitcnt lgkmcnt(0)
	v_add_f32_e32 v73, v143, v71
	v_rcp_f32_e32 v76, v75
	ds_bpermute_b32 v74, v166, v73
	v_and_b32_e32 v71, 0xffff0000, v177
	v_pk_fma_f32 v[66:67], v[66:67], v[80:81], v[70:71] op_sel_hi:[1,0,1]
	v_fma_f32 v71, -v75, v76, 1.0
	v_fmac_f32_e32 v76, v71, v76
	v_div_scale_f32 v71, vcc, 1.0, v72, 1.0
	s_waitcnt lgkmcnt(0)
	v_add_f32_e32 v70, v73, v74
	v_mul_f32_e32 v73, v71, v76
	v_fma_f32 v74, -v75, v73, v71
	v_fmac_f32_e32 v73, v74, v76
	v_fma_f32 v71, -v75, v73, v71
	v_div_fmas_f32 v71, v71, v76, v73
	v_div_fixup_f32 v71, v71, v72, 1.0
	v_div_scale_f32 v72, s[0:1], v70, v70, v71
	v_rcp_f32_e32 v73, v72
	v_cvt_pk_bf16_f32 v196, v68, v69
	v_lshlrev_b32_e32 v68, 16, v184
	v_and_b32_e32 v69, 0xffff0000, v184
	v_pk_fma_f32 v[64:65], v[64:65], v[80:81], v[68:69] op_sel_hi:[1,0,1]
	v_cvt_pk_bf16_f32 v194, v66, v67
	v_lshlrev_b32_e32 v68, 16, v157
	v_cvt_pk_bf16_f32 v197, v64, v65
	v_fma_f32 v64, -v72, v73, 1.0
	v_fmac_f32_e32 v73, v64, v73
	v_div_scale_f32 v64, vcc, v71, v70, v71
	v_mul_f32_e32 v65, v64, v73
	v_fma_f32 v66, -v72, v65, v64
	v_fmac_f32_e32 v65, v66, v73
	v_fma_f32 v64, -v72, v65, v64
	v_div_fmas_f32 v64, v64, v73, v65
	v_div_fixup_f32 v64, v64, v70, v71
	v_cmp_lt_f32_e32 vcc, 0, v70
	v_and_b32_e32 v69, 0xffff0000, v157
	v_lshlrev_b32_e32 v66, 16, v158
	v_cndmask_b32_e32 v64, 0, v64, vcc
	v_pk_fma_f32 v[62:63], v[62:63], v[64:65], v[68:69] op_sel_hi:[1,0,1]
	v_and_b32_e32 v67, 0xffff0000, v158
	v_cvt_pk_bf16_f32 v192, v62, v63
	v_lshlrev_b32_e32 v62, 16, v159
	v_and_b32_e32 v63, 0xffff0000, v159
	v_pk_fma_f32 v[58:59], v[58:59], v[64:65], v[62:63] op_sel_hi:[1,0,1]
	v_pk_fma_f32 v[60:61], v[60:61], v[64:65], v[66:67] op_sel_hi:[1,0,1]
	v_cvt_pk_bf16_f32 v190, v58, v59
	v_lshlrev_b32_e32 v58, 16, v161
	v_and_b32_e32 v59, 0xffff0000, v161
	v_cvt_pk_bf16_f32 v193, v60, v61
	v_lshlrev_b32_e32 v60, 16, v160
	v_and_b32_e32 v61, 0xffff0000, v160
	v_pk_fma_f32 v[54:55], v[54:55], v[64:65], v[58:59] op_sel_hi:[1,0,1]
	v_pk_fma_f32 v[56:57], v[56:57], v[64:65], v[60:61] op_sel_hi:[1,0,1]
	v_cvt_pk_bf16_f32 v187, v54, v55
	s_waitcnt vmcnt(0)
	v_lshlrev_b32_e32 v54, 16, v125
	v_cvt_pk_bf16_f32 v191, v56, v57
	v_lshlrev_b32_e32 v56, 16, v174
	v_and_b32_e32 v57, 0xffff0000, v174
	v_mul_f32_e32 v54, 0xbfb8aa3b, v54
	v_pk_fma_f32 v[52:53], v[52:53], v[64:65], v[56:57] op_sel_hi:[1,0,1]
	v_exp_f32_e32 v56, v54
	ds_bpermute_b32 v55, v167, v142
	v_lshlrev_b32_e32 v54, 16, v175
	v_cvt_pk_bf16_f32 v188, v52, v53
	v_add_f32_e32 v56, 1.0, v56
	v_div_scale_f32 v59, s[0:1], v56, v56, 1.0
	s_waitcnt lgkmcnt(0)
	v_add_f32_e32 v57, v142, v55
	v_rcp_f32_e32 v60, v59
	ds_bpermute_b32 v58, v166, v57
	v_and_b32_e32 v55, 0xffff0000, v175
	v_pk_fma_f32 v[50:51], v[50:51], v[64:65], v[54:55] op_sel_hi:[1,0,1]
	v_fma_f32 v55, -v59, v60, 1.0
	v_fmac_f32_e32 v60, v55, v60
	v_div_scale_f32 v55, vcc, 1.0, v56, 1.0
	s_waitcnt lgkmcnt(0)
	v_add_f32_e32 v54, v57, v58
	v_mul_f32_e32 v57, v55, v60
	v_fma_f32 v58, -v59, v57, v55
	v_fmac_f32_e32 v57, v58, v60
	v_fma_f32 v55, -v59, v57, v55
	v_div_fmas_f32 v55, v55, v60, v57
	v_div_fixup_f32 v55, v55, v56, 1.0
	v_div_scale_f32 v56, s[0:1], v54, v54, v55
	v_rcp_f32_e32 v57, v56
	v_lshlrev_b32_e32 v52, 16, v176
	v_and_b32_e32 v53, 0xffff0000, v176
	v_pk_fma_f32 v[48:49], v[48:49], v[64:65], v[52:53] op_sel_hi:[1,0,1]
	v_cvt_pk_bf16_f32 v186, v50, v51
	v_and_b32_e32 v51, 0xffff0000, v155
	v_cvt_pk_bf16_f32 v189, v48, v49
	v_fma_f32 v48, -v56, v57, 1.0
	v_fmac_f32_e32 v57, v48, v57
	v_div_scale_f32 v48, vcc, v55, v54, v55
	v_mul_f32_e32 v49, v48, v57
	v_fma_f32 v50, -v56, v49, v48
	v_fmac_f32_e32 v49, v50, v57
	v_fma_f32 v48, -v56, v49, v48
	v_div_fmas_f32 v48, v48, v57, v49
	v_div_fixup_f32 v48, v48, v54, v55
	v_cmp_lt_f32_e32 vcc, 0, v54
	v_lshlrev_b32_e32 v50, 16, v155
	v_lshlrev_b32_e32 v52, 16, v156
	v_cndmask_b32_e32 v48, 0, v48, vcc
	v_and_b32_e32 v53, 0xffff0000, v156
	v_pk_fma_f32 v[46:47], v[46:47], v[48:49], v[52:53] op_sel_hi:[1,0,1]
	v_pk_fma_f32 v[44:45], v[44:45], v[48:49], v[50:51] op_sel_hi:[1,0,1]
	v_cvt_pk_bf16_f32 v185, v46, v47
	v_lshlrev_b32_e32 v46, 16, v154
	v_cvt_pk_bf16_f32 v184, v44, v45
	v_lshlrev_b32_e32 v44, 16, v153
	v_and_b32_e32 v45, 0xffff0000, v153
	v_and_b32_e32 v47, 0xffff0000, v154
	v_pk_fma_f32 v[42:43], v[42:43], v[48:49], v[46:47] op_sel_hi:[1,0,1]
	v_pk_fma_f32 v[40:41], v[40:41], v[48:49], v[44:45] op_sel_hi:[1,0,1]
	v_cvt_pk_bf16_f32 v179, v42, v43
	v_lshlrev_b32_e32 v42, 16, v151
	v_cvt_pk_bf16_f32 v178, v40, v41
	v_lshlrev_b32_e32 v40, 16, v150
	v_and_b32_e32 v41, 0xffff0000, v150
	v_and_b32_e32 v43, 0xffff0000, v151
	s_add_i32 s0, s80, 0xfffffe01
	v_pk_fma_f32 v[38:39], v[38:39], v[48:49], v[42:43] op_sel_hi:[1,0,1]
	v_pk_fma_f32 v[36:37], v[36:37], v[48:49], v[40:41] op_sel_hi:[1,0,1]
	s_lshr_b32 s0, s0, 5
	v_cvt_pk_bf16_f32 v176, v36, v37
	v_cvt_pk_bf16_f32 v177, v38, v39
	v_lshlrev_b32_e32 v36, 16, v148
	v_and_b32_e32 v37, 0xffff0000, v148
	v_lshlrev_b32_e32 v38, 16, v149
	v_and_b32_e32 v39, 0xffff0000, v149
	s_cmpk_gt_u32 s80, 0x1ff
	v_pk_fma_f32 v[88:89], v[88:89], v[120:121], v[98:99] op_sel_hi:[1,0,1]
	v_pk_fma_f32 v[86:87], v[86:87], v[120:121], v[108:109] op_sel_hi:[1,0,1]
	v_pk_fma_f32 v[82:83], v[82:83], v[120:121], v[110:111] op_sel_hi:[1,0,1]
	v_pk_fma_f32 v[78:79], v[78:79], v[80:81], v[114:115] op_sel_hi:[1,0,1]
	v_pk_fma_f32 v[34:35], v[34:35], v[48:49], v[38:39] op_sel_hi:[1,0,1]
	v_pk_fma_f32 v[32:33], v[32:33], v[48:49], v[36:37] op_sel_hi:[1,0,1]
	s_cselect_b32 s48, s0, 0
	v_cvt_pk_bf16_f32 v209, v92, v93
	v_cvt_pk_bf16_f32 v208, v94, v95
	v_cvt_pk_bf16_f32 v207, v88, v89
	v_cvt_pk_bf16_f32 v206, v90, v91
	v_cvt_pk_bf16_f32 v205, v86, v87
	v_cvt_pk_bf16_f32 v202, v82, v83
	v_cvt_pk_bf16_f32 v200, v78, v79
	v_cvt_pk_bf16_f32 v175, v32, v33
	v_cvt_pk_bf16_f32 v174, v34, v35
	s_cmp_gt_u32 s48, s71
	v_mov_b32_e32 v143, v139
	v_mov_b32_e32 v142, v139
	v_mov_b32_e32 v83, v139
	v_mov_b32_e32 v82, v139
	v_mov_b32_e32 v81, v139
	v_mov_b32_e32 v80, v139
	v_mov_b32_e32 v67, v139
	v_mov_b32_e32 v66, v139
	v_mov_b32_e32 v65, v139
	v_mov_b32_e32 v64, v139
	v_mov_b32_e32 v51, v139
	v_mov_b32_e32 v50, v139
	v_mov_b32_e32 v49, v139
	v_mov_b32_e32 v48, v139
	v_mov_b32_e32 v35, v139
	v_mov_b32_e32 v34, v139
	v_mov_b32_e32 v33, v139
	v_mov_b32_e32 v32, v139
	v_mov_b32_e32 v87, v139
	v_mov_b32_e32 v86, v139
	v_mov_b32_e32 v85, v139
	v_mov_b32_e32 v84, v139
	v_mov_b32_e32 v71, v139
	v_mov_b32_e32 v70, v139
	v_mov_b32_e32 v69, v139
	v_mov_b32_e32 v68, v139
	v_mov_b32_e32 v55, v139
	v_mov_b32_e32 v54, v139
	v_mov_b32_e32 v53, v139
	v_mov_b32_e32 v52, v139
	v_mov_b32_e32 v39, v139
	v_mov_b32_e32 v38, v139
	v_mov_b32_e32 v37, v139
	v_mov_b32_e32 v36, v139
	v_mov_b32_e32 v91, v139
	v_mov_b32_e32 v90, v139
	v_mov_b32_e32 v89, v139
	v_mov_b32_e32 v88, v139
	v_mov_b32_e32 v75, v139
	v_mov_b32_e32 v74, v139
	v_mov_b32_e32 v73, v139
	v_mov_b32_e32 v72, v139
	v_mov_b32_e32 v59, v139
	v_mov_b32_e32 v58, v139
	v_mov_b32_e32 v57, v139
	v_mov_b32_e32 v56, v139
	v_mov_b32_e32 v47, v139
	v_mov_b32_e32 v46, v139
	v_mov_b32_e32 v45, v139
	v_mov_b32_e32 v44, v139
	v_mov_b32_e32 v95, v139
	v_mov_b32_e32 v94, v139
	v_mov_b32_e32 v93, v139
	v_mov_b32_e32 v92, v139
	v_mov_b32_e32 v79, v139
	v_mov_b32_e32 v78, v139
	v_mov_b32_e32 v77, v139
	v_mov_b32_e32 v76, v139
	v_mov_b32_e32 v63, v139
	v_mov_b32_e32 v62, v139
	v_mov_b32_e32 v61, v139
	v_mov_b32_e32 v60, v139
	v_mov_b32_e32 v43, v139
	v_mov_b32_e32 v42, v139
	v_mov_b32_e32 v41, v139
	v_mov_b32_e32 v40, v139
	s_cbranch_scc1 .LBB0_369
	v_add3_u32 v32, s80, -7, v128
	s_add_i32 s0, s48, -1
	v_sub_u32_e32 v32, v32, v130
	s_lshl_b32 s1, s48, 5
	s_lshl_b64 s[6:7], s[48:49], 12
	v_subrev_u32_e32 v210, s1, v32
	v_lshl_add_u64 v[32:33], s[6:7], 0, v[144:145]
	s_add_u32 s6, s87, s76
	v_lshl_add_u64 v[32:33], v[32:33], 0, v[132:133]
	s_addc_u32 s7, s88, s77
	v_mov_b32_e32 v40, 0
	v_add3_u32 v211, v130, s1, 7
	v_lshl_add_u64 v[144:145], s[6:7], 0, v[32:33]
	v_lshl_add_u32 v252, v181, 4, s79
	s_add_i32 s98, s79, 0x1000
	s_add_i32 s99, s79, 0x2000
	v_add_co_u32_e32 v250, vcc, 0xfefff400, v144
	s_nop 1
	v_addc_co_u32_e32 v251, vcc, -1, v145, vcc
	v_add_co_u32_e32 v248, vcc, 0xfffff400, v144
	s_nop 1
	v_addc_co_u32_e32 v249, vcc, -1, v145, vcc
	s_mov_b32 m0, s98
	s_nop 0
	global_load_lds_dwordx4 v[250:251], off
	global_load_lds_dwordx4 v[250:251], off offset:1024
	global_load_lds_dwordx4 v[250:251], off offset:2048
	global_load_lds_dwordx4 v[250:251], off offset:3072
	s_mov_b32 m0, s99
	s_nop 0
	global_load_lds_dwordx4 v[248:249], off
	global_load_lds_dwordx4 v[248:249], off offset:1024
	global_load_lds_dwordx4 v[248:249], off offset:2048
	global_load_lds_dwordx4 v[248:249], off offset:3072
	v_mov_b32_e32 v41, v40
	v_mov_b32_e32 v42, v40
	v_mov_b32_e32 v43, v40
	v_mov_b32_e32 v44, v40
	v_mov_b32_e32 v45, v40
	v_mov_b32_e32 v46, v40
	v_mov_b32_e32 v47, v40
	v_mov_b32_e32 v36, v40
	v_mov_b32_e32 v37, v40
	v_mov_b32_e32 v38, v40
	v_mov_b32_e32 v39, v40
	v_mov_b32_e32 v32, v40
	v_mov_b32_e32 v33, v40
	v_mov_b32_e32 v34, v40
	v_mov_b32_e32 v35, v40
	v_mov_b32_e32 v60, v40
	v_mov_b32_e32 v61, v40
	v_mov_b32_e32 v62, v40
	v_mov_b32_e32 v63, v40
	v_mov_b32_e32 v56, v40
	v_mov_b32_e32 v57, v40
	v_mov_b32_e32 v58, v40
	v_mov_b32_e32 v59, v40
	v_mov_b32_e32 v52, v40
	v_mov_b32_e32 v53, v40
	v_mov_b32_e32 v54, v40
	v_mov_b32_e32 v55, v40
	v_mov_b32_e32 v48, v40
	v_mov_b32_e32 v49, v40
	v_mov_b32_e32 v50, v40
	v_mov_b32_e32 v51, v40
	v_mov_b32_e32 v76, v40
	v_mov_b32_e32 v77, v40
	v_mov_b32_e32 v78, v40
	v_mov_b32_e32 v79, v40
	v_mov_b32_e32 v72, v40
	v_mov_b32_e32 v73, v40
	v_mov_b32_e32 v74, v40
	v_mov_b32_e32 v75, v40
	v_mov_b32_e32 v68, v40
	v_mov_b32_e32 v69, v40
	v_mov_b32_e32 v70, v40
	v_mov_b32_e32 v71, v40
	v_mov_b32_e32 v64, v40
	v_mov_b32_e32 v65, v40
	v_mov_b32_e32 v66, v40
	v_mov_b32_e32 v67, v40
	v_mov_b32_e32 v92, v40
	v_mov_b32_e32 v93, v40
	v_mov_b32_e32 v94, v40
	v_mov_b32_e32 v95, v40
	v_mov_b32_e32 v88, v40
	v_mov_b32_e32 v89, v40
	v_mov_b32_e32 v90, v40
	v_mov_b32_e32 v91, v40
	v_mov_b32_e32 v84, v40
	v_mov_b32_e32 v85, v40
	v_mov_b32_e32 v86, v40
	v_mov_b32_e32 v87, v40
	v_mov_b32_e32 v80, v40
	v_mov_b32_e32 v81, v40
	v_mov_b32_e32 v82, v40
	v_mov_b32_e32 v83, v40
	v_mov_b32_e32 v142, v40
	v_mov_b32_e32 v143, v40
	v_mov_b32_e32 v138, v40
	v_mov_b32_e32 v139, v40
.LBB0_402:
	v_add_u32_e32 v128, -7, v211
	v_add_co_u32_e32 v250, vcc, 0xff000400, v144
	s_nop 1
	v_addc_co_u32_e32 v251, vcc, -1, v145, vcc
	v_add_co_u32_e32 v248, vcc, 0x400, v144
	s_nop 1
	v_addc_co_u32_e32 v249, vcc, 0, v145, vcc
	s_waitcnt vmcnt(0)
	ds_read_b128 v[120:123], v252 offset:4096
	ds_read_b128 v[124:127], v252 offset:5120
	ds_read_b128 v[116:119], v252 offset:6144
	ds_read_b128 v[112:115], v252 offset:7168
	ds_read_b128 v[96:99], v252 offset:8192
	ds_read_b128 v[100:103], v252 offset:9216
	ds_read_b128 v[104:107], v252 offset:10240
	ds_read_b128 v[108:111], v252 offset:11264
	v_add_u32_e32 v129, 7, v210
	v_cmp_le_i32_e32 vcc, v128, v134
	v_cmp_gt_i32_e64 s[6:7], s91, v129
	s_and_b64 s[12:13], vcc, s[6:7]
	v_cmp_lt_i32_e32 vcc, v128, v134
	v_add_u32_e32 v128, 6, v210
	v_cmp_gt_i32_e64 s[6:7], s91, v128
	v_cvt_f32_i32_e32 v150, v128
	v_add_u32_e32 v128, -5, v211
	s_and_b64 s[14:15], vcc, s[6:7]
	v_cmp_le_i32_e32 vcc, v128, v134
	v_add_u32_e32 v128, 5, v210
	v_cmp_gt_i32_e64 s[6:7], s91, v128
	v_cvt_f32_i32_e32 v158, v128
	v_add_u32_e32 v128, -4, v211
	s_and_b64 s[16:17], vcc, s[6:7]
	v_cmp_le_i32_e32 vcc, v128, v134
	v_add_u32_e32 v128, 4, v210
	v_cmp_gt_i32_e64 s[6:7], s91, v128
	v_cvt_f32_i32_e32 v212, v128
	v_add_u32_e32 v128, -3, v211
	s_and_b64 s[18:19], vcc, s[6:7]
	v_cmp_le_i32_e32 vcc, v128, v134
	v_add_u32_e32 v128, 3, v210
	v_cmp_gt_i32_e64 s[6:7], s91, v128
	v_cvt_f32_i32_e32 v148, v128
	v_add_u32_e32 v128, -2, v211
	s_and_b64 s[10:11], vcc, s[6:7]
	v_cmp_le_i32_e32 vcc, v128, v134
	v_add_u32_e32 v128, 2, v210
	v_cmp_gt_i32_e64 s[6:7], s91, v128
	v_cvt_f32_i32_e32 v154, v128
	v_add_u32_e32 v128, -1, v211
	s_and_b64 s[8:9], vcc, s[6:7]
	v_cmp_le_i32_e32 vcc, v128, v134
	v_add_u32_e32 v128, 1, v210
	v_cvt_f32_i32_e32 v146, v129
	v_cmp_gt_i32_e64 s[6:7], s91, v128
	v_cvt_f32_i32_e32 v152, v128
	v_cvt_f32_i32_e32 v132, v210
	s_and_b64 s[6:7], vcc, s[6:7]
	v_cmp_le_i32_e32 vcc, v211, v134
	v_cmp_gt_i32_e64 s[20:21], s91, v210
	s_and_b64 vcc, vcc, s[20:21]
	s_add_i32 s0, s0, 1
	v_subrev_u32_e32 v210, 32, v210
	v_add_u32_e32 v211, 32, v211
	v_lshl_add_u64 v[144:145], v[144:145], 0, s[52:53]
	s_cmp_lt_u32 s0, s71
	s_waitcnt lgkmcnt(0)
	s_mov_b32 m0, s98
	s_nop 0
	global_load_lds_dwordx4 v[250:251], off
	global_load_lds_dwordx4 v[250:251], off offset:1024
	global_load_lds_dwordx4 v[250:251], off offset:2048
	global_load_lds_dwordx4 v[250:251], off offset:3072
	s_mov_b32 m0, s99
	s_nop 0
	global_load_lds_dwordx4 v[248:249], off
	global_load_lds_dwordx4 v[248:249], off offset:1024
	global_load_lds_dwordx4 v[248:249], off offset:2048
	global_load_lds_dwordx4 v[248:249], off offset:3072
	v_mfma_f32_16x16x32_bf16 v[128:131], v[120:123], v[0:3], 0
	v_mfma_f32_16x16x32_bf16 v[128:131], v[124:127], v[4:7], v[128:131]
	v_mfma_f32_16x16x32_bf16 v[214:217], v[120:123], v[8:11], 0
	v_mfma_f32_16x16x32_bf16 v[214:217], v[124:127], v[12:15], v[214:217]
	s_nop 5
	v_add_f32_e32 v128, 0xc1800000, v128
	v_fma_f32 v128, -v170, v146, v128
	v_exp_f32_e32 v147, v128
	v_add_f32_e32 v128, 0xc1800000, v129
	v_fma_f32 v128, -v170, v150, v128
	v_exp_f32_e32 v149, v128
	v_cndmask_b32_e64 v157, 0, v147, s[12:13]
	v_add_f32_e32 v147, 0xc1800000, v214
	v_fma_f32 v147, -v171, v146, v147
	v_exp_f32_e32 v147, v147
	v_add_f32_e32 v128, 0xc1800000, v130
	v_fma_f32 v128, -v170, v158, v128
	v_exp_f32_e32 v151, v128
	v_cndmask_b32_e64 v156, 0, v147, s[12:13]
	v_add_f32_e32 v147, 0xc1800000, v215
	v_fma_f32 v147, -v171, v150, v147
	v_exp_f32_e32 v147, v147
	v_add_f32_e32 v128, 0xc1800000, v131
	v_fma_f32 v128, -v170, v212, v128
	v_exp_f32_e32 v153, v128
	v_cndmask_b32_e64 v160, 0, v147, s[14:15]
	v_add_f32_e32 v147, 0xc1800000, v216
	v_fma_f32 v147, -v171, v158, v147
	v_exp_f32_e32 v147, v147
	v_cndmask_b32_e64 v161, 0, v149, s[14:15]
	v_pk_add_f32 v[230:231], v[156:157], 0 op_sel_hi:[1,0]
	v_cndmask_b32_e64 v219, 0, v151, s[16:17]
	v_cndmask_b32_e64 v218, 0, v147, s[16:17]
	v_add_f32_e32 v147, 0xc1800000, v217
	v_fma_f32 v147, -v171, v212, v147
	v_exp_f32_e32 v147, v147
	v_pk_add_f32 v[214:215], v[160:161], v[230:231]
	v_cndmask_b32_e64 v221, 0, v153, s[18:19]
	v_pk_add_f32 v[214:215], v[218:219], v[214:215]
	v_cndmask_b32_e64 v220, 0, v147, s[18:19]
	v_pk_add_f32 v[230:231], v[220:221], v[214:215]
	v_mfma_f32_16x16x32_bf16 v[214:217], v[116:119], v[8:11], 0
	v_mfma_f32_16x16x32_bf16 v[214:217], v[112:115], v[12:15], v[214:217]
	v_mfma_f32_16x16x32_bf16 v[128:131], v[116:119], v[0:3], 0
	v_mfma_f32_16x16x32_bf16 v[128:131], v[112:115], v[4:7], v[128:131]
	s_nop 5
	v_add_f32_e32 v147, 0xc1800000, v214
	v_fma_f32 v147, -v171, v148, v147
	v_exp_f32_e32 v147, v147
	s_nop 0
	v_cndmask_b32_e64 v222, 0, v147, s[10:11]
	v_add_f32_e32 v147, 0xc1800000, v215
	v_fma_f32 v147, -v171, v154, v147
	v_exp_f32_e32 v147, v147
	v_add_f32_e32 v128, 0xc1800000, v128
	v_add_f32_e32 v129, 0xc1800000, v129
	v_add_f32_e32 v130, 0xc1800000, v130
	v_cndmask_b32_e64 v224, 0, v147, s[8:9]
	v_add_f32_e32 v147, 0xc1800000, v216
	v_fma_f32 v147, -v171, v152, v147
	v_exp_f32_e32 v147, v147
	v_add_f32_e32 v131, 0xc1800000, v131
	v_fma_f32 v128, -v170, v148, v128
	v_fma_f32 v129, -v170, v154, v129
	v_fma_f32 v130, -v170, v152, v130
	v_fma_f32 v131, -v170, v132, v131
	v_cndmask_b32_e64 v226, 0, v147, s[6:7]
	v_add_f32_e32 v147, 0xc1800000, v217
	v_exp_f32_e32 v128, v128
	v_exp_f32_e32 v129, v129
	v_exp_f32_e32 v130, v130
	v_exp_f32_e32 v131, v131
	v_fma_f32 v147, -v171, v132, v147
	v_exp_f32_e32 v147, v147
	v_cndmask_b32_e64 v223, 0, v128, s[10:11]
	v_cndmask_b32_e64 v225, 0, v129, s[8:9]
	v_cndmask_b32_e64 v227, 0, v130, s[6:7]
	v_cndmask_b32_e32 v229, 0, v131, vcc
	v_cvt_pk_bf16_f32 v128, v157, v161
	v_cvt_pk_bf16_f32 v129, v219, v221
	v_cvt_pk_bf16_f32 v130, v223, v225
	v_cvt_pk_bf16_f32 v131, v227, v229
	v_cndmask_b32_e32 v228, 0, v147, vcc
	v_mfma_f32_16x16x32_bf16 v[80:83], v[96:99], v[128:131], v[80:83]
	v_add_f32_e64 v230, v222, v230
	v_add_f32_e64 v231, v223, v231
	v_pk_add_f32 v[214:215], v[224:225], v[230:231]
	v_mfma_f32_16x16x32_bf16 v[84:87], v[100:103], v[128:131], v[84:87]
	v_add_f32_e64 v214, v226, v214
	v_add_f32_e64 v215, v227, v215
	v_pk_add_f32 v[214:215], v[228:229], v[214:215]
	v_mfma_f32_16x16x32_bf16 v[88:91], v[104:107], v[128:131], v[88:91]
	v_add_f32_e64 v138, v138, v214
	v_add_f32_e64 v139, v139, v215
	v_mfma_f32_16x16x32_bf16 v[92:95], v[108:111], v[128:131], v[92:95]
	v_cvt_pk_bf16_f32 v128, v156, v160
	v_cvt_pk_bf16_f32 v129, v218, v220
	v_cvt_pk_bf16_f32 v130, v222, v224
	v_cvt_pk_bf16_f32 v131, v226, v228
	s_nop 0
	v_mfma_f32_16x16x32_bf16 v[64:67], v[96:99], v[128:131], v[64:67]
	v_mfma_f32_16x16x32_bf16 v[68:71], v[100:103], v[128:131], v[68:71]
	v_mfma_f32_16x16x32_bf16 v[72:75], v[104:107], v[128:131], v[72:75]
	v_mfma_f32_16x16x32_bf16 v[76:79], v[108:111], v[128:131], v[76:79]
	v_mfma_f32_16x16x32_bf16 v[128:131], v[120:123], v[16:19], 0
	v_mfma_f32_16x16x32_bf16 v[128:131], v[124:127], v[20:23], v[128:131]
	v_mfma_f32_16x16x32_bf16 v[120:123], v[120:123], v[24:27], 0
	v_mfma_f32_16x16x32_bf16 v[120:123], v[124:127], v[28:31], v[120:123]
	s_nop 5
	v_add_f32_e32 v128, 0xc1800000, v128
	v_fma_f32 v128, -v172, v146, v128
	v_exp_f32_e32 v147, v128
	v_add_f32_e32 v128, 0xc1800000, v129
	v_fma_f32 v128, -v172, v150, v128
	v_exp_f32_e32 v149, v128
	v_add_f32_e32 v128, 0xc1800000, v130
	v_fma_f32 v128, -v172, v158, v128
	v_exp_f32_e32 v151, v128
	v_add_f32_e32 v128, 0xc1800000, v131
	v_fma_f32 v128, -v172, v212, v128
	v_exp_f32_e32 v153, v128
	v_mfma_f32_16x16x32_bf16 v[128:131], v[116:119], v[16:19], 0
	v_add_f32_e32 v120, 0xc1800000, v120
	v_fma_f32 v120, -v173, v146, v120
	v_exp_f32_e32 v120, v120
	v_mfma_f32_16x16x32_bf16 v[116:119], v[116:119], v[24:27], 0
	v_add_f32_e32 v122, 0xc1800000, v122
	v_fma_f32 v122, -v173, v158, v122
	v_exp_f32_e32 v122, v122
	v_mfma_f32_16x16x32_bf16 v[128:131], v[112:115], v[20:23], v[128:131]
	v_cndmask_b32_e64 v156, 0, v120, s[12:13]
	v_add_f32_e32 v120, 0xc1800000, v121
	v_fma_f32 v120, -v173, v150, v120
	v_mfma_f32_16x16x32_bf16 v[112:115], v[112:115], v[28:31], v[116:119]
	v_exp_f32_e32 v120, v120
	v_cndmask_b32_e64 v146, 0, v122, s[16:17]
	v_add_f32_e32 v122, 0xc1800000, v123
	s_nop 0
	v_add_f32_e32 v128, 0xc1800000, v128
	v_fma_f32 v122, -v173, v212, v122
	s_nop 1
	v_add_f32_e32 v112, 0xc1800000, v112
	v_fma_f32 v112, -v173, v148, v112
	v_exp_f32_e32 v112, v112
	v_add_f32_e32 v114, 0xc1800000, v114
	v_fma_f32 v114, -v173, v152, v114
	v_exp_f32_e32 v114, v114
	v_fma_f32 v128, -v172, v148, v128
	v_add_f32_e32 v129, 0xc1800000, v129
	v_exp_f32_e32 v122, v122
	v_cndmask_b32_e64 v148, 0, v112, s[10:11]
	v_add_f32_e32 v112, 0xc1800000, v113
	v_exp_f32_e32 v128, v128
	v_fma_f32 v129, -v172, v154, v129
	v_add_f32_e32 v130, 0xc1800000, v130
	v_cndmask_b32_e64 v157, 0, v147, s[12:13]
	v_fma_f32 v112, -v173, v154, v112
	v_exp_f32_e32 v129, v129
	v_fma_f32 v130, -v172, v152, v130
	v_add_f32_e32 v131, 0xc1800000, v131
	v_cndmask_b32_e64 v161, 0, v149, s[14:15]
	v_pk_add_f32 v[124:125], v[156:157], 0 op_sel_hi:[1,0]
	v_cndmask_b32_e64 v160, 0, v120, s[14:15]
	v_exp_f32_e32 v112, v112
	v_cndmask_b32_e64 v152, 0, v114, s[6:7]
	v_add_f32_e32 v114, 0xc1800000, v115
	v_exp_f32_e32 v130, v130
	v_fma_f32 v131, -v172, v132, v131
	v_cndmask_b32_e64 v147, 0, v151, s[16:17]
	v_pk_add_f32 v[120:121], v[160:161], v[124:125]
	v_fma_f32 v114, -v173, v132, v114
	v_exp_f32_e32 v131, v131
	v_cndmask_b32_e64 v151, 0, v153, s[18:19]
	v_pk_add_f32 v[120:121], v[146:147], v[120:121]
	v_cndmask_b32_e64 v150, 0, v122, s[18:19]
	v_exp_f32_e32 v114, v114
	v_cndmask_b32_e64 v149, 0, v128, s[10:11]
	v_pk_add_f32 v[120:121], v[150:151], v[120:121]
	v_cndmask_b32_e64 v155, 0, v129, s[8:9]
	v_pk_add_f32 v[116:117], v[148:149], v[120:121]
	v_cndmask_b32_e64 v154, 0, v112, s[8:9]
	v_cndmask_b32_e64 v153, 0, v130, s[6:7]
	v_pk_add_f32 v[112:113], v[154:155], v[116:117]
	v_cndmask_b32_e32 v159, 0, v131, vcc
	v_pk_add_f32 v[112:113], v[152:153], v[112:113]
	v_cndmask_b32_e32 v158, 0, v114, vcc
	v_pk_add_f32 v[112:113], v[158:159], v[112:113]
	v_cvt_pk_bf16_f32 v128, v157, v161
	v_cvt_pk_bf16_f32 v129, v147, v151
	v_cvt_pk_bf16_f32 v130, v149, v155
	v_cvt_pk_bf16_f32 v131, v153, v159
	v_cvt_pk_bf16_f32 v114, v148, v154
	s_nop 0
	v_pk_add_f32 v[142:143], v[142:143], v[112:113]
	v_mfma_f32_16x16x32_bf16 v[48:51], v[96:99], v[128:131], v[48:51]
	v_cvt_pk_bf16_f32 v112, v156, v160
	v_cvt_pk_bf16_f32 v113, v146, v150
	v_cvt_pk_bf16_f32 v115, v152, v158
	v_mfma_f32_16x16x32_bf16 v[52:55], v[100:103], v[128:131], v[52:55]
	v_mfma_f32_16x16x32_bf16 v[56:59], v[104:107], v[128:131], v[56:59]
	v_mfma_f32_16x16x32_bf16 v[60:63], v[108:111], v[128:131], v[60:63]
	v_mfma_f32_16x16x32_bf16 v[32:35], v[96:99], v[112:115], v[32:35]
	v_mfma_f32_16x16x32_bf16 v[36:39], v[100:103], v[112:115], v[36:39]
	v_mfma_f32_16x16x32_bf16 v[44:47], v[104:107], v[112:115], v[44:47]
	v_mfma_f32_16x16x32_bf16 v[40:43], v[108:111], v[112:115], v[40:43]
	s_cbranch_scc1 .LBB0_402
	s_branch .LBB0_369

	.amdhsa_kernel _Z10fwd_kernel7KParams
		.amdhsa_group_segment_fixed_size 0
		.amdhsa_private_segment_fixed_size 0
		.amdhsa_kernarg_size 472
		.amdhsa_user_sgpr_count 2
		.amdhsa_user_sgpr_dispatch_ptr 0
		.amdhsa_user_sgpr_queue_ptr 0
		.amdhsa_user_sgpr_kernarg_segment_ptr 1
		.amdhsa_user_sgpr_dispatch_id 0
		.amdhsa_user_sgpr_kernarg_preload_length 0
		.amdhsa_user_sgpr_kernarg_preload_offset 0
		.amdhsa_user_sgpr_private_segment_size 0
		.amdhsa_uses_dynamic_stack 0
		.amdhsa_enable_private_segment 0
		.amdhsa_system_sgpr_workgroup_id_x 1
		.amdhsa_system_sgpr_workgroup_id_y 0
		.amdhsa_system_sgpr_workgroup_id_z 0
		.amdhsa_system_sgpr_workgroup_info 0
		.amdhsa_system_vgpr_workitem_id 2
		.amdhsa_next_free_vgpr 256
		.amdhsa_next_free_sgpr 100
		.amdhsa_accum_offset 256
		.amdhsa_reserve_vcc 1
		.amdhsa_float_round_mode_32 0
		.amdhsa_float_round_mode_16_64 0
		.amdhsa_float_denorm_mode_32 3
		.amdhsa_float_denorm_mode_16_64 3
		.amdhsa_dx10_clamp 1
		.amdhsa_ieee_mode 1
		.amdhsa_fp16_overflow 0
		.amdhsa_tg_split 0
		.amdhsa_exception_fp_ieee_invalid_op 0
		.amdhsa_exception_fp_denorm_src 0
		.amdhsa_exception_fp_ieee_div_zero 0
		.amdhsa_exception_fp_ieee_overflow 0
		.amdhsa_exception_fp_ieee_underflow 0
		.amdhsa_exception_fp_ieee_inexact 0
		.amdhsa_exception_int_div_zero 0
	.end_amdhsa_kernel
